# priority raise for waves 4..7 scoped to the token-mixer phases only
# baseline (speedup 1.0000x reference)
; __global__ void __launch_bounds__(NTHREADS, 2) mk_fwd(Args args) {
;     ...
;             for (int it = blk; it < 256; it += G) p2_block(lds, PROJ, ATT, SGU, args.in[3] + l * 64, args.in[4] + l * 64, args.in[5] + l * 16, COS, SIN, args.in[6] + l * 1024, args.in[7] + l * 1024,
;                                                            args.in[8] + (size_t)l * 8 * 16384, args.in[9] + l * 1024, it, tid);
.LBB0_326:
	s_andn2_b64 vcc, exec, s[0:1]
	v_readlane_b32 s0, v248, 2
	v_readlane_b32 s1, v248, 3
	s_nop 1
	v_cndmask_b32_e64 v0, 0, 1, s[0:1]
	v_cmp_ne_u32_e64 s[70:71], 1, v0
	s_cbranch_vccnz .LBB0_413
	s_and_b64 vcc, exec, s[70:71]
	s_cbranch_vccnz .LBB0_346
	s_lshl_b32 s4, s64, 6
	v_readlane_b32 s36, v250, 2
	s_lshl_b64 s[0:1], s[4:5], 2
	v_readlane_b32 s38, v250, 4
	v_readlane_b32 s42, v250, 8
	v_readlane_b32 s39, v250, 5
	v_readlane_b32 s43, v250, 9
	s_add_u32 s38, s42, s0
	v_readlane_b32 s44, v250, 10
	s_addc_u32 s39, s43, s1
	v_readlane_b32 s45, v250, 11
	s_add_u32 s0, s44, s0
	s_addc_u32 s1, s45, s1
	s_lshl_b32 s4, s64, 4
	v_readlane_b32 s46, v250, 12
	s_lshl_b64 s[6:7], s[4:5], 2
	v_readlane_b32 s47, v250, 13
	s_add_u32 s63, s46, s6
	s_addc_u32 s78, s47, s7
	s_lshl_b32 s4, s64, 10
	v_readlane_b32 s48, v250, 14
	s_lshl_b64 s[6:7], s[4:5], 2
	v_readlane_b32 s37, v250, 3
	v_readlane_b32 s49, v250, 15
	s_add_u32 s36, s48, s6
	v_readlane_b32 s50, v250, 16
	s_addc_u32 s37, s49, s7
	v_readlane_b32 s40, v250, 6
	v_readlane_b32 s41, v250, 7
	v_readlane_b32 s51, v250, 17
	s_add_u32 s18, s50, s6
	s_addc_u32 s19, s51, s7
	s_lshl_b64 s[16:17], s[64:65], 19
	v_readlane_b32 s40, v250, 18
	v_readlane_b32 s41, v250, 19
	s_add_u32 s20, s40, s16
	v_readlane_b32 s42, v250, 20
	s_addc_u32 s21, s41, s17
	v_readlane_b32 s43, v250, 21
	s_add_u32 s22, s42, s6
	s_addc_u32 s23, s43, s7
	s_mov_b32 s2, s85
	v_readfirstlane_b32 vcc_lo, v204
	s_nop 3
	s_lshr_b32 vcc_lo, vcc_lo, 6
	s_cmp_ge_u32 vcc_lo, 4
	s_cbranch_scc0 .Lprio_tm_in
	s_setprio 1
.Lprio_tm_in:
	v_readlane_b32 s44, v250, 22
	v_readlane_b32 s45, v250, 23
	v_readlane_b32 s46, v250, 24
	v_readlane_b32 s47, v250, 25
	v_readlane_b32 s48, v250, 26
	v_readlane_b32 s49, v250, 27
	v_readlane_b32 s50, v250, 28
	v_readlane_b32 s51, v250, 29
	v_readlane_b32 s52, v250, 30
	v_readlane_b32 s53, v250, 31
	v_readlane_b32 s54, v250, 32
	v_readlane_b32 s55, v250, 33
	s_branch .LBB0_330

; __device__ __forceinline__ unsigned cvt_pk_bf16(float lo, float hi) { unsigned r; asm volatile("v_cvt_pk_bf16_f32 %0, %1, %2" : "=v"(r) : "v"(lo), "v"(hi)); return r; }
; __device__ __forceinline__ float bf_lo(unsigned w) { return __uint_as_float(w << 16); }
; __device__ __forceinline__ float bf_hi(unsigned w) { return __uint_as_float(w & 0xffff0000u); }
; __device__ __forceinline__ float gelu_f(float x) { const float y2 = 1.5957691216057308f * x * (1.0f + 0.044715f * x * x); return x * sigmoid_f(y2); }
; __device__ __forceinline__ void p2_block(LAS unsigned char* lds, const bf16_t* __restrict__ PROJ, bf16_t* __restrict__ ATT, bf16_t* __restrict__ SGU, const float* __restrict__ qn, const float* __restrict__ kn, ...
;     ...
;         const float bias = bsp[gg * 128 + irow];
;         const size_t grow = (size_t)b * pg8::SEQ + n * 128 + irow;
;         const bf16_t* up = PROJ + grow * pg8::IN_W + pg8::C_U + gg * 128 + 4 * fq; bf16_t* op = SGU + grow * 1024 + gg * 128 + 4 * fq;
; #pragma unroll
;         for (int dt = 0; dt < 8; ++dt) { const u32x2 uw = *(const u32x2*)(up + 16 * dt);
;             const float u0 = gelu_f(bf_lo(uw.x)), u1 = gelu_f(bf_hi(uw.x)), u2 = gelu_f(bf_lo(uw.y)), u3 = gelu_f(bf_hi(uw.y));
;             u32x2 ow; ow.x = cvt_pk_bf16(u0 * (acc[dt][0] + bias), u1 * (acc[dt][1] + bias)); ow.y = cvt_pk_bf16(u2 * (acc[dt][2] + bias), u3 * (acc[dt][3] + bias)); *(u32x2*)(op + 16 * dt) = ow; }
.Lsgu_epi:
	v_mov_b32_e32 v197, 0xbdd2d3e7
	s_waitcnt vmcnt(0)
	v_lshlrev_b32_e32 v34, 16, v218
	v_and_b32_e32 v35, 0xffff0000, v218
	v_lshlrev_b32_e32 v36, 16, v219
	v_and_b32_e32 v37, 0xffff0000, v219
	v_mul_f32_e32 v38, v34, v34
	v_mul_f32_e32 v39, v35, v35
	v_mul_f32_e32 v40, v36, v36
	v_mul_f32_e32 v41, v37, v37
	v_fmaak_f32 v38, v38, v197, 0xc0135761
	v_fmaak_f32 v39, v39, v197, 0xc0135761
	v_fmaak_f32 v40, v40, v197, 0xc0135761
	v_fmaak_f32 v41, v41, v197, 0xc0135761
	v_mul_f32_e32 v38, v38, v34
	v_mul_f32_e32 v39, v39, v35
	v_mul_f32_e32 v40, v40, v36
	v_mul_f32_e32 v41, v41, v37
	v_exp_f32_e32 v38, v38
	v_exp_f32_e32 v39, v39
	v_exp_f32_e32 v40, v40
	v_exp_f32_e32 v41, v41
	v_add_f32_e32 v38, 1.0, v38
	v_add_f32_e32 v39, 1.0, v39
	v_add_f32_e32 v40, 1.0, v40
	v_add_f32_e32 v41, 1.0, v41
	v_rcp_f32_e32 v38, v38
	v_rcp_f32_e32 v39, v39
	v_rcp_f32_e32 v40, v40
	v_rcp_f32_e32 v41, v41
	v_mul_f32_e32 v34, v38, v34
	v_mul_f32_e32 v35, v39, v35
	v_mul_f32_e32 v36, v40, v36
	v_mul_f32_e32 v37, v41, v37
	v_mul_f32_e32 v46, v2, v34
	v_mul_f32_e32 v47, v3, v35
	v_mul_f32_e32 v48, v4, v36
	v_mul_f32_e32 v49, v5, v37
	v_cvt_pk_bf16_f32 v50, v46, v47
	v_cvt_pk_bf16_f32 v51, v48, v49
	global_store_dwordx2 v182, v[50:51], s[12:13] offset:0
	v_lshlrev_b32_e32 v34, 16, v220
	v_and_b32_e32 v35, 0xffff0000, v220
	v_lshlrev_b32_e32 v36, 16, v221
	v_and_b32_e32 v37, 0xffff0000, v221
	v_mul_f32_e32 v38, v34, v34
	v_mul_f32_e32 v39, v35, v35
	v_mul_f32_e32 v40, v36, v36
	v_mul_f32_e32 v41, v37, v37
	v_fmaak_f32 v38, v38, v197, 0xc0135761
	v_fmaak_f32 v39, v39, v197, 0xc0135761
	v_fmaak_f32 v40, v40, v197, 0xc0135761
	v_fmaak_f32 v41, v41, v197, 0xc0135761
	v_mul_f32_e32 v38, v38, v34
	v_mul_f32_e32 v39, v39, v35
	v_mul_f32_e32 v40, v40, v36
	v_mul_f32_e32 v41, v41, v37
	v_exp_f32_e32 v38, v38
	v_exp_f32_e32 v39, v39
	v_exp_f32_e32 v40, v40
	v_exp_f32_e32 v41, v41
	v_add_f32_e32 v38, 1.0, v38
	v_add_f32_e32 v39, 1.0, v39
	v_add_f32_e32 v40, 1.0, v40
	v_add_f32_e32 v41, 1.0, v41
	v_rcp_f32_e32 v38, v38
	v_rcp_f32_e32 v39, v39
	v_rcp_f32_e32 v40, v40
	v_rcp_f32_e32 v41, v41
	v_mul_f32_e32 v34, v38, v34
	v_mul_f32_e32 v35, v39, v35
	v_mul_f32_e32 v36, v40, v36
	v_mul_f32_e32 v37, v41, v37
	v_mul_f32_e32 v46, v6, v34
	v_mul_f32_e32 v47, v7, v35
	v_mul_f32_e32 v48, v8, v36
	v_mul_f32_e32 v49, v9, v37
	v_cvt_pk_bf16_f32 v50, v46, v47
	v_cvt_pk_bf16_f32 v51, v48, v49
	global_store_dwordx2 v182, v[50:51], s[12:13] offset:32
	v_lshlrev_b32_e32 v34, 16, v222
	v_and_b32_e32 v35, 0xffff0000, v222
	v_lshlrev_b32_e32 v36, 16, v223
	v_and_b32_e32 v37, 0xffff0000, v223
	v_mul_f32_e32 v38, v34, v34
	v_mul_f32_e32 v39, v35, v35
	v_mul_f32_e32 v40, v36, v36
	v_mul_f32_e32 v41, v37, v37
	v_fmaak_f32 v38, v38, v197, 0xc0135761
	v_fmaak_f32 v39, v39, v197, 0xc0135761
	v_fmaak_f32 v40, v40, v197, 0xc0135761
	v_fmaak_f32 v41, v41, v197, 0xc0135761
	v_mul_f32_e32 v38, v38, v34
	v_mul_f32_e32 v39, v39, v35
	v_mul_f32_e32 v40, v40, v36
	v_mul_f32_e32 v41, v41, v37
	v_exp_f32_e32 v38, v38
	v_exp_f32_e32 v39, v39
	v_exp_f32_e32 v40, v40
	v_exp_f32_e32 v41, v41
	v_add_f32_e32 v38, 1.0, v38
	v_add_f32_e32 v39, 1.0, v39
	v_add_f32_e32 v40, 1.0, v40
	v_add_f32_e32 v41, 1.0, v41
	v_rcp_f32_e32 v38, v38
	v_rcp_f32_e32 v39, v39
	v_rcp_f32_e32 v40, v40
	v_rcp_f32_e32 v41, v41
	v_mul_f32_e32 v34, v38, v34
	v_mul_f32_e32 v35, v39, v35
	v_mul_f32_e32 v36, v40, v36
	v_mul_f32_e32 v37, v41, v37
	v_mul_f32_e32 v46, v10, v34
	v_mul_f32_e32 v47, v11, v35
	v_mul_f32_e32 v48, v12, v36
	v_mul_f32_e32 v49, v13, v37
	v_cvt_pk_bf16_f32 v50, v46, v47
	v_cvt_pk_bf16_f32 v51, v48, v49
	global_store_dwordx2 v182, v[50:51], s[12:13] offset:64
	v_lshlrev_b32_e32 v34, 16, v224
	v_and_b32_e32 v35, 0xffff0000, v224
	v_lshlrev_b32_e32 v36, 16, v225
	v_and_b32_e32 v37, 0xffff0000, v225
	v_mul_f32_e32 v38, v34, v34
	v_mul_f32_e32 v39, v35, v35
	v_mul_f32_e32 v40, v36, v36
	v_mul_f32_e32 v41, v37, v37
	v_fmaak_f32 v38, v38, v197, 0xc0135761
	v_fmaak_f32 v39, v39, v197, 0xc0135761
	v_fmaak_f32 v40, v40, v197, 0xc0135761
	v_fmaak_f32 v41, v41, v197, 0xc0135761
	v_mul_f32_e32 v38, v38, v34
	v_mul_f32_e32 v39, v39, v35
	v_mul_f32_e32 v40, v40, v36
	v_mul_f32_e32 v41, v41, v37
	v_exp_f32_e32 v38, v38
	v_exp_f32_e32 v39, v39
	v_exp_f32_e32 v40, v40
	v_exp_f32_e32 v41, v41
	v_add_f32_e32 v38, 1.0, v38
	v_add_f32_e32 v39, 1.0, v39
	v_add_f32_e32 v40, 1.0, v40
	v_add_f32_e32 v41, 1.0, v41
	v_rcp_f32_e32 v38, v38
	v_rcp_f32_e32 v39, v39
	v_rcp_f32_e32 v40, v40
	v_rcp_f32_e32 v41, v41
	v_mul_f32_e32 v34, v38, v34
	v_mul_f32_e32 v35, v39, v35
	v_mul_f32_e32 v36, v40, v36
	v_mul_f32_e32 v37, v41, v37
	v_mul_f32_e32 v46, v14, v34
	v_mul_f32_e32 v47, v15, v35
	v_mul_f32_e32 v48, v16, v36
	v_mul_f32_e32 v49, v17, v37
	v_cvt_pk_bf16_f32 v50, v46, v47
	v_cvt_pk_bf16_f32 v51, v48, v49
	global_store_dwordx2 v182, v[50:51], s[12:13] offset:96
	v_lshlrev_b32_e32 v34, 16, v226
	v_and_b32_e32 v35, 0xffff0000, v226
	v_lshlrev_b32_e32 v36, 16, v227
	v_and_b32_e32 v37, 0xffff0000, v227
	v_mul_f32_e32 v38, v34, v34
	v_mul_f32_e32 v39, v35, v35
	v_mul_f32_e32 v40, v36, v36
	v_mul_f32_e32 v41, v37, v37
	v_fmaak_f32 v38, v38, v197, 0xc0135761
	v_fmaak_f32 v39, v39, v197, 0xc0135761
	v_fmaak_f32 v40, v40, v197, 0xc0135761
	v_fmaak_f32 v41, v41, v197, 0xc0135761
	v_mul_f32_e32 v38, v38, v34
	v_mul_f32_e32 v39, v39, v35
	v_mul_f32_e32 v40, v40, v36
	v_mul_f32_e32 v41, v41, v37
	v_exp_f32_e32 v38, v38
	v_exp_f32_e32 v39, v39
	v_exp_f32_e32 v40, v40
	v_exp_f32_e32 v41, v41
	v_add_f32_e32 v38, 1.0, v38
	v_add_f32_e32 v39, 1.0, v39
	v_add_f32_e32 v40, 1.0, v40
	v_add_f32_e32 v41, 1.0, v41
	v_rcp_f32_e32 v38, v38
	v_rcp_f32_e32 v39, v39
	v_rcp_f32_e32 v40, v40
; __device__ __forceinline__ unsigned cvt_pk_bf16(float lo, float hi) { unsigned r; asm volatile("v_cvt_pk_bf16_f32 %0, %1, %2" : "=v"(r) : "v"(lo), "v"(hi)); return r; }
; __device__ __forceinline__ float bf_lo(unsigned w) { return __uint_as_float(w << 16); }
; __device__ __forceinline__ float bf_hi(unsigned w) { return __uint_as_float(w & 0xffff0000u); }
; __device__ __forceinline__ float gelu_f(float x) { const float y2 = 1.5957691216057308f * x * (1.0f + 0.044715f * x * x); return x * sigmoid_f(y2); }
; __device__ __forceinline__ float sigmoid_f(float v) { return __builtin_amdgcn_rcpf(1.0f + __expf(-v)); }
; __device__ __forceinline__ void p2_block(LAS unsigned char* lds, const bf16_t* __restrict__ PROJ, bf16_t* __restrict__ ATT, bf16_t* __restrict__ SGU, const float* __restrict__ qn, const float* __restrict__ kn, ...
;     ...
;         for (int dt = 0; dt < 8; ++dt) { const u32x2 uw = *(const u32x2*)(up + 16 * dt);
;             const float u0 = gelu_f(bf_lo(uw.x)), u1 = gelu_f(bf_hi(uw.x)), u2 = gelu_f(bf_lo(uw.y)), u3 = gelu_f(bf_hi(uw.y));
;             u32x2 ow; ow.x = cvt_pk_bf16(u0 * (acc[dt][0] + bias), u1 * (acc[dt][1] + bias)); ow.y = cvt_pk_bf16(u2 * (acc[dt][2] + bias), u3 * (acc[dt][3] + bias)); *(u32x2*)(op + 16 * dt) = ow; }
	v_rcp_f32_e32 v41, v41
	v_mul_f32_e32 v34, v38, v34
	v_mul_f32_e32 v35, v39, v35
	v_mul_f32_e32 v36, v40, v36
	v_mul_f32_e32 v37, v41, v37
	v_mul_f32_e32 v46, v18, v34
	v_mul_f32_e32 v47, v19, v35
	v_mul_f32_e32 v48, v20, v36
	v_mul_f32_e32 v49, v21, v37
	v_cvt_pk_bf16_f32 v50, v46, v47
	v_cvt_pk_bf16_f32 v51, v48, v49
	global_store_dwordx2 v182, v[50:51], s[12:13] offset:128
	v_lshlrev_b32_e32 v34, 16, v228
	v_and_b32_e32 v35, 0xffff0000, v228
	v_lshlrev_b32_e32 v36, 16, v229
	v_and_b32_e32 v37, 0xffff0000, v229
	v_mul_f32_e32 v38, v34, v34
	v_mul_f32_e32 v39, v35, v35
	v_mul_f32_e32 v40, v36, v36
	v_mul_f32_e32 v41, v37, v37
	v_fmaak_f32 v38, v38, v197, 0xc0135761
	v_fmaak_f32 v39, v39, v197, 0xc0135761
	v_fmaak_f32 v40, v40, v197, 0xc0135761
	v_fmaak_f32 v41, v41, v197, 0xc0135761
	v_mul_f32_e32 v38, v38, v34
	v_mul_f32_e32 v39, v39, v35
	v_mul_f32_e32 v40, v40, v36
	v_mul_f32_e32 v41, v41, v37
	v_exp_f32_e32 v38, v38
	v_exp_f32_e32 v39, v39
	v_exp_f32_e32 v40, v40
	v_exp_f32_e32 v41, v41
	v_add_f32_e32 v38, 1.0, v38
	v_add_f32_e32 v39, 1.0, v39
	v_add_f32_e32 v40, 1.0, v40
	v_add_f32_e32 v41, 1.0, v41
	v_rcp_f32_e32 v38, v38
	v_rcp_f32_e32 v39, v39
	v_rcp_f32_e32 v40, v40
	v_rcp_f32_e32 v41, v41
	v_mul_f32_e32 v34, v38, v34
	v_mul_f32_e32 v35, v39, v35
	v_mul_f32_e32 v36, v40, v36
	v_mul_f32_e32 v37, v41, v37
	v_mul_f32_e32 v46, v22, v34
	v_mul_f32_e32 v47, v23, v35
	v_mul_f32_e32 v48, v24, v36
	v_mul_f32_e32 v49, v25, v37
	v_cvt_pk_bf16_f32 v50, v46, v47
	v_cvt_pk_bf16_f32 v51, v48, v49
	global_store_dwordx2 v182, v[50:51], s[12:13] offset:160
	v_lshlrev_b32_e32 v34, 16, v230
	v_and_b32_e32 v35, 0xffff0000, v230
	v_lshlrev_b32_e32 v36, 16, v231
	v_and_b32_e32 v37, 0xffff0000, v231
	v_mul_f32_e32 v38, v34, v34
	v_mul_f32_e32 v39, v35, v35
	v_mul_f32_e32 v40, v36, v36
	v_mul_f32_e32 v41, v37, v37
	v_fmaak_f32 v38, v38, v197, 0xc0135761
	v_fmaak_f32 v39, v39, v197, 0xc0135761
	v_fmaak_f32 v40, v40, v197, 0xc0135761
	v_fmaak_f32 v41, v41, v197, 0xc0135761
	v_mul_f32_e32 v38, v38, v34
	v_mul_f32_e32 v39, v39, v35
	v_mul_f32_e32 v40, v40, v36
	v_mul_f32_e32 v41, v41, v37
	v_exp_f32_e32 v38, v38
	v_exp_f32_e32 v39, v39
	v_exp_f32_e32 v40, v40
	v_exp_f32_e32 v41, v41
	v_add_f32_e32 v38, 1.0, v38
	v_add_f32_e32 v39, 1.0, v39
	v_add_f32_e32 v40, 1.0, v40
	v_add_f32_e32 v41, 1.0, v41
	v_rcp_f32_e32 v38, v38
	v_rcp_f32_e32 v39, v39
	v_rcp_f32_e32 v40, v40
	v_rcp_f32_e32 v41, v41
	v_mul_f32_e32 v34, v38, v34
	v_mul_f32_e32 v35, v39, v35
	v_mul_f32_e32 v36, v40, v36
	v_mul_f32_e32 v37, v41, v37
	v_mul_f32_e32 v46, v26, v34
	v_mul_f32_e32 v47, v27, v35
	v_mul_f32_e32 v48, v28, v36
	v_mul_f32_e32 v49, v29, v37
	v_cvt_pk_bf16_f32 v50, v46, v47
	v_cvt_pk_bf16_f32 v51, v48, v49
	global_store_dwordx2 v182, v[50:51], s[12:13] offset:192
	v_lshlrev_b32_e32 v34, 16, v232
	v_and_b32_e32 v35, 0xffff0000, v232
	v_lshlrev_b32_e32 v36, 16, v233
	v_and_b32_e32 v37, 0xffff0000, v233
	v_mul_f32_e32 v38, v34, v34
	v_mul_f32_e32 v39, v35, v35
	v_mul_f32_e32 v40, v36, v36
	v_mul_f32_e32 v41, v37, v37
	v_fmaak_f32 v38, v38, v197, 0xc0135761
	v_fmaak_f32 v39, v39, v197, 0xc0135761
	v_fmaak_f32 v40, v40, v197, 0xc0135761
	v_fmaak_f32 v41, v41, v197, 0xc0135761
	v_mul_f32_e32 v38, v38, v34
	v_mul_f32_e32 v39, v39, v35
	v_mul_f32_e32 v40, v40, v36
	v_mul_f32_e32 v41, v41, v37
	v_exp_f32_e32 v38, v38
	v_exp_f32_e32 v39, v39
	v_exp_f32_e32 v40, v40
	v_exp_f32_e32 v41, v41
	v_add_f32_e32 v38, 1.0, v38
	v_add_f32_e32 v39, 1.0, v39
	v_add_f32_e32 v40, 1.0, v40
	v_add_f32_e32 v41, 1.0, v41
	v_rcp_f32_e32 v38, v38
	v_rcp_f32_e32 v39, v39
	v_rcp_f32_e32 v40, v40
	v_rcp_f32_e32 v41, v41
	v_mul_f32_e32 v34, v38, v34
	v_mul_f32_e32 v35, v39, v35
	v_mul_f32_e32 v36, v40, v36
	v_mul_f32_e32 v37, v41, v37
	v_mul_f32_e32 v46, v30, v34
	v_mul_f32_e32 v47, v31, v35
	v_mul_f32_e32 v48, v32, v36
	v_mul_f32_e32 v49, v33, v37
	v_cvt_pk_bf16_f32 v50, v46, v47
	v_cvt_pk_bf16_f32 v51, v48, v49
	global_store_dwordx2 v182, v[50:51], s[12:13] offset:224
	v_lshlrev_b32_e32 v34, 16, v234
	v_and_b32_e32 v35, 0xffff0000, v234
	v_lshlrev_b32_e32 v36, 16, v235
	v_and_b32_e32 v37, 0xffff0000, v235
	v_mul_f32_e32 v38, v34, v34
	v_mul_f32_e32 v39, v35, v35
	v_mul_f32_e32 v40, v36, v36
	v_mul_f32_e32 v41, v37, v37
	v_fmaak_f32 v38, v38, v197, 0xc0135761
	v_fmaak_f32 v39, v39, v197, 0xc0135761
	v_fmaak_f32 v40, v40, v197, 0xc0135761
	v_fmaak_f32 v41, v41, v197, 0xc0135761
	v_mul_f32_e32 v38, v38, v34
	v_mul_f32_e32 v39, v39, v35
	v_mul_f32_e32 v40, v40, v36
	v_mul_f32_e32 v41, v41, v37
	v_exp_f32_e32 v38, v38
	v_exp_f32_e32 v39, v39
	v_exp_f32_e32 v40, v40
	v_exp_f32_e32 v41, v41
	v_add_f32_e32 v38, 1.0, v38
	v_add_f32_e32 v39, 1.0, v39
	v_add_f32_e32 v40, 1.0, v40
	v_add_f32_e32 v41, 1.0, v41
	v_rcp_f32_e32 v38, v38
	v_rcp_f32_e32 v39, v39
	v_rcp_f32_e32 v40, v40
	v_rcp_f32_e32 v41, v41
	v_mul_f32_e32 v34, v38, v34
	v_mul_f32_e32 v35, v39, v35
	v_mul_f32_e32 v36, v40, v36
	v_mul_f32_e32 v37, v41, v37
	v_mul_f32_e32 v46, v114, v34
	v_mul_f32_e32 v47, v115, v35
	v_mul_f32_e32 v48, v116, v36
	v_mul_f32_e32 v49, v117, v37
	v_cvt_pk_bf16_f32 v50, v46, v47
	v_cvt_pk_bf16_f32 v51, v48, v49
	global_store_dwordx2 v182, v[50:51], s[12:13] offset:256
	v_lshlrev_b32_e32 v34, 16, v236
	v_and_b32_e32 v35, 0xffff0000, v236
	v_lshlrev_b32_e32 v36, 16, v237
	v_and_b32_e32 v37, 0xffff0000, v237
	v_mul_f32_e32 v38, v34, v34
	v_mul_f32_e32 v39, v35, v35
	v_mul_f32_e32 v40, v36, v36
	v_mul_f32_e32 v41, v37, v37
	v_fmaak_f32 v38, v38, v197, 0xc0135761
	v_fmaak_f32 v39, v39, v197, 0xc0135761
	v_fmaak_f32 v40, v40, v197, 0xc0135761
	v_fmaak_f32 v41, v41, v197, 0xc0135761
	v_mul_f32_e32 v38, v38, v34
	v_mul_f32_e32 v39, v39, v35
; __device__ __forceinline__ unsigned cvt_pk_bf16(float lo, float hi) { unsigned r; asm volatile("v_cvt_pk_bf16_f32 %0, %1, %2" : "=v"(r) : "v"(lo), "v"(hi)); return r; }
; __device__ __forceinline__ float bf_lo(unsigned w) { return __uint_as_float(w << 16); }
; __device__ __forceinline__ float bf_hi(unsigned w) { return __uint_as_float(w & 0xffff0000u); }
; __device__ __forceinline__ float gelu_f(float x) { const float y2 = 1.5957691216057308f * x * (1.0f + 0.044715f * x * x); return x * sigmoid_f(y2); }
; __device__ __forceinline__ float sigmoid_f(float v) { return __builtin_amdgcn_rcpf(1.0f + __expf(-v)); }
; __device__ __forceinline__ void p2_block(LAS unsigned char* lds, const bf16_t* __restrict__ PROJ, bf16_t* __restrict__ ATT, bf16_t* __restrict__ SGU, const float* __restrict__ qn, const float* __restrict__ kn, ...
;     ...
;         for (int dt = 0; dt < 8; ++dt) { const u32x2 uw = *(const u32x2*)(up + 16 * dt);
;             const float u0 = gelu_f(bf_lo(uw.x)), u1 = gelu_f(bf_hi(uw.x)), u2 = gelu_f(bf_lo(uw.y)), u3 = gelu_f(bf_hi(uw.y));
;             u32x2 ow; ow.x = cvt_pk_bf16(u0 * (acc[dt][0] + bias), u1 * (acc[dt][1] + bias)); ow.y = cvt_pk_bf16(u2 * (acc[dt][2] + bias), u3 * (acc[dt][3] + bias)); *(u32x2*)(op + 16 * dt) = ow; }
	v_mul_f32_e32 v40, v40, v36
	v_mul_f32_e32 v41, v41, v37
	v_exp_f32_e32 v38, v38
	v_exp_f32_e32 v39, v39
	v_exp_f32_e32 v40, v40
	v_exp_f32_e32 v41, v41
	v_add_f32_e32 v38, 1.0, v38
	v_add_f32_e32 v39, 1.0, v39
	v_add_f32_e32 v40, 1.0, v40
	v_add_f32_e32 v41, 1.0, v41
	v_rcp_f32_e32 v38, v38
	v_rcp_f32_e32 v39, v39
	v_rcp_f32_e32 v40, v40
	v_rcp_f32_e32 v41, v41
	v_mul_f32_e32 v34, v38, v34
	v_mul_f32_e32 v35, v39, v35
	v_mul_f32_e32 v36, v40, v36
	v_mul_f32_e32 v37, v41, v37
	v_mul_f32_e32 v46, v118, v34
	v_mul_f32_e32 v47, v119, v35
	v_mul_f32_e32 v48, v120, v36
	v_mul_f32_e32 v49, v121, v37
	v_cvt_pk_bf16_f32 v50, v46, v47
	v_cvt_pk_bf16_f32 v51, v48, v49
	global_store_dwordx2 v182, v[50:51], s[12:13] offset:288
	v_lshlrev_b32_e32 v34, 16, v238
	v_and_b32_e32 v35, 0xffff0000, v238
	v_lshlrev_b32_e32 v36, 16, v239
	v_and_b32_e32 v37, 0xffff0000, v239
	v_mul_f32_e32 v38, v34, v34
	v_mul_f32_e32 v39, v35, v35
	v_mul_f32_e32 v40, v36, v36
	v_mul_f32_e32 v41, v37, v37
	v_fmaak_f32 v38, v38, v197, 0xc0135761
	v_fmaak_f32 v39, v39, v197, 0xc0135761
	v_fmaak_f32 v40, v40, v197, 0xc0135761
	v_fmaak_f32 v41, v41, v197, 0xc0135761
	v_mul_f32_e32 v38, v38, v34
	v_mul_f32_e32 v39, v39, v35
	v_mul_f32_e32 v40, v40, v36
	v_mul_f32_e32 v41, v41, v37
	v_exp_f32_e32 v38, v38
	v_exp_f32_e32 v39, v39
	v_exp_f32_e32 v40, v40
	v_exp_f32_e32 v41, v41
	v_add_f32_e32 v38, 1.0, v38
	v_add_f32_e32 v39, 1.0, v39
	v_add_f32_e32 v40, 1.0, v40
	v_add_f32_e32 v41, 1.0, v41
	v_rcp_f32_e32 v38, v38
	v_rcp_f32_e32 v39, v39
	v_rcp_f32_e32 v40, v40
	v_rcp_f32_e32 v41, v41
	v_mul_f32_e32 v34, v38, v34
	v_mul_f32_e32 v35, v39, v35
	v_mul_f32_e32 v36, v40, v36
	v_mul_f32_e32 v37, v41, v37
	v_mul_f32_e32 v46, v122, v34
	v_mul_f32_e32 v47, v123, v35
	v_mul_f32_e32 v48, v124, v36
	v_mul_f32_e32 v49, v125, v37
	v_cvt_pk_bf16_f32 v50, v46, v47
	v_cvt_pk_bf16_f32 v51, v48, v49
	global_store_dwordx2 v182, v[50:51], s[12:13] offset:320
	v_lshlrev_b32_e32 v34, 16, v240
	v_and_b32_e32 v35, 0xffff0000, v240
	v_lshlrev_b32_e32 v36, 16, v241
	v_and_b32_e32 v37, 0xffff0000, v241
	v_mul_f32_e32 v38, v34, v34
	v_mul_f32_e32 v39, v35, v35
	v_mul_f32_e32 v40, v36, v36
	v_mul_f32_e32 v41, v37, v37
	v_fmaak_f32 v38, v38, v197, 0xc0135761
	v_fmaak_f32 v39, v39, v197, 0xc0135761
	v_fmaak_f32 v40, v40, v197, 0xc0135761
	v_fmaak_f32 v41, v41, v197, 0xc0135761
	v_mul_f32_e32 v38, v38, v34
	v_mul_f32_e32 v39, v39, v35
	v_mul_f32_e32 v40, v40, v36
	v_mul_f32_e32 v41, v41, v37
	v_exp_f32_e32 v38, v38
	v_exp_f32_e32 v39, v39
	v_exp_f32_e32 v40, v40
	v_exp_f32_e32 v41, v41
	v_add_f32_e32 v38, 1.0, v38
	v_add_f32_e32 v39, 1.0, v39
	v_add_f32_e32 v40, 1.0, v40
	v_add_f32_e32 v41, 1.0, v41
	v_rcp_f32_e32 v38, v38
	v_rcp_f32_e32 v39, v39
	v_rcp_f32_e32 v40, v40
	v_rcp_f32_e32 v41, v41
	v_mul_f32_e32 v34, v38, v34
	v_mul_f32_e32 v35, v39, v35
	v_mul_f32_e32 v36, v40, v36
	v_mul_f32_e32 v37, v41, v37
	v_mul_f32_e32 v46, v126, v34
	v_mul_f32_e32 v47, v127, v35
	v_mul_f32_e32 v48, v128, v36
	v_mul_f32_e32 v49, v129, v37
	v_cvt_pk_bf16_f32 v50, v46, v47
	v_cvt_pk_bf16_f32 v51, v48, v49
	global_store_dwordx2 v182, v[50:51], s[12:13] offset:352
	v_lshlrev_b32_e32 v34, 16, v242
	v_and_b32_e32 v35, 0xffff0000, v242
	v_lshlrev_b32_e32 v36, 16, v243
	v_and_b32_e32 v37, 0xffff0000, v243
	v_mul_f32_e32 v38, v34, v34
	v_mul_f32_e32 v39, v35, v35
	v_mul_f32_e32 v40, v36, v36
	v_mul_f32_e32 v41, v37, v37
	v_fmaak_f32 v38, v38, v197, 0xc0135761
	v_fmaak_f32 v39, v39, v197, 0xc0135761
	v_fmaak_f32 v40, v40, v197, 0xc0135761
	v_fmaak_f32 v41, v41, v197, 0xc0135761
	v_mul_f32_e32 v38, v38, v34
	v_mul_f32_e32 v39, v39, v35
	v_mul_f32_e32 v40, v40, v36
	v_mul_f32_e32 v41, v41, v37
	v_exp_f32_e32 v38, v38
	v_exp_f32_e32 v39, v39
	v_exp_f32_e32 v40, v40
	v_exp_f32_e32 v41, v41
	v_add_f32_e32 v38, 1.0, v38
	v_add_f32_e32 v39, 1.0, v39
	v_add_f32_e32 v40, 1.0, v40
	v_add_f32_e32 v41, 1.0, v41
	v_rcp_f32_e32 v38, v38
	v_rcp_f32_e32 v39, v39
	v_rcp_f32_e32 v40, v40
	v_rcp_f32_e32 v41, v41
	v_mul_f32_e32 v34, v38, v34
	v_mul_f32_e32 v35, v39, v35
; __device__ __forceinline__ unsigned cvt_pk_bf16(float lo, float hi) { unsigned r; asm volatile("v_cvt_pk_bf16_f32 %0, %1, %2" : "=v"(r) : "v"(lo), "v"(hi)); return r; }
; __device__ __forceinline__ float bf_lo(unsigned w) { return __uint_as_float(w << 16); }
; __device__ __forceinline__ float bf_hi(unsigned w) { return __uint_as_float(w & 0xffff0000u); }
; __device__ __forceinline__ float gelu_f(float x) { const float y2 = 1.5957691216057308f * x * (1.0f + 0.044715f * x * x); return x * sigmoid_f(y2); }
; __device__ __forceinline__ void p2_block(LAS unsigned char* lds, const bf16_t* __restrict__ PROJ, bf16_t* __restrict__ ATT, bf16_t* __restrict__ SGU, const float* __restrict__ qn, const float* __restrict__ kn, ...
;     ...
;         for (int dt = 0; dt < 8; ++dt) { const u32x2 uw = *(const u32x2*)(up + 16 * dt);
;             const float u0 = gelu_f(bf_lo(uw.x)), u1 = gelu_f(bf_hi(uw.x)), u2 = gelu_f(bf_lo(uw.y)), u3 = gelu_f(bf_hi(uw.y));
;             u32x2 ow; ow.x = cvt_pk_bf16(u0 * (acc[dt][0] + bias), u1 * (acc[dt][1] + bias)); ow.y = cvt_pk_bf16(u2 * (acc[dt][2] + bias), u3 * (acc[dt][3] + bias)); *(u32x2*)(op + 16 * dt) = ow; }
;     }
;     __syncthreads();
; __global__ void __launch_bounds__(NTHREADS, 2) mk_fwd(Args args) {
;     ...
;             for (int it = blk; it < 256; it += G) p2_block(lds, PROJ, ATT, SGU, args.in[3] + l * 64, args.in[4] + l * 64, args.in[5] + l * 16, COS, SIN, args.in[6] + l * 1024, args.in[7] + l * 1024,
;                                                            args.in[8] + (size_t)l * 8 * 16384, args.in[9] + l * 1024, it, tid);
	v_mul_f32_e32 v36, v40, v36
	v_mul_f32_e32 v37, v41, v37
	v_mul_f32_e32 v46, v130, v34
	v_mul_f32_e32 v47, v131, v35
	v_mul_f32_e32 v48, v132, v36
	v_mul_f32_e32 v49, v133, v37
	v_cvt_pk_bf16_f32 v50, v46, v47
	v_cvt_pk_bf16_f32 v51, v48, v49
	global_store_dwordx2 v182, v[50:51], s[12:13] offset:384
	v_lshlrev_b32_e32 v34, 16, v244
	v_and_b32_e32 v35, 0xffff0000, v244
	v_lshlrev_b32_e32 v36, 16, v245
	v_and_b32_e32 v37, 0xffff0000, v245
	v_mul_f32_e32 v38, v34, v34
	v_mul_f32_e32 v39, v35, v35
	v_mul_f32_e32 v40, v36, v36
	v_mul_f32_e32 v41, v37, v37
	v_fmaak_f32 v38, v38, v197, 0xc0135761
	v_fmaak_f32 v39, v39, v197, 0xc0135761
	v_fmaak_f32 v40, v40, v197, 0xc0135761
	v_fmaak_f32 v41, v41, v197, 0xc0135761
	v_mul_f32_e32 v38, v38, v34
	v_mul_f32_e32 v39, v39, v35
	v_mul_f32_e32 v40, v40, v36
	v_mul_f32_e32 v41, v41, v37
	v_exp_f32_e32 v38, v38
	v_exp_f32_e32 v39, v39
	v_exp_f32_e32 v40, v40
	v_exp_f32_e32 v41, v41
	v_add_f32_e32 v38, 1.0, v38
	v_add_f32_e32 v39, 1.0, v39
	v_add_f32_e32 v40, 1.0, v40
	v_add_f32_e32 v41, 1.0, v41
	v_rcp_f32_e32 v38, v38
	v_rcp_f32_e32 v39, v39
	v_rcp_f32_e32 v40, v40
	v_rcp_f32_e32 v41, v41
	v_mul_f32_e32 v34, v38, v34
	v_mul_f32_e32 v35, v39, v35
	v_mul_f32_e32 v36, v40, v36
	v_mul_f32_e32 v37, v41, v37
	v_mul_f32_e32 v46, v134, v34
	v_mul_f32_e32 v47, v135, v35
	v_mul_f32_e32 v48, v136, v36
	v_mul_f32_e32 v49, v137, v37
	v_cvt_pk_bf16_f32 v50, v46, v47
	v_cvt_pk_bf16_f32 v51, v48, v49
	global_store_dwordx2 v182, v[50:51], s[12:13] offset:416
	v_lshlrev_b32_e32 v34, 16, v200
	v_and_b32_e32 v35, 0xffff0000, v200
	v_lshlrev_b32_e32 v36, 16, v201
	v_and_b32_e32 v37, 0xffff0000, v201
	v_mul_f32_e32 v38, v34, v34
	v_mul_f32_e32 v39, v35, v35
	v_mul_f32_e32 v40, v36, v36
	v_mul_f32_e32 v41, v37, v37
	v_fmaak_f32 v38, v38, v197, 0xc0135761
	v_fmaak_f32 v39, v39, v197, 0xc0135761
	v_fmaak_f32 v40, v40, v197, 0xc0135761
	v_fmaak_f32 v41, v41, v197, 0xc0135761
	v_mul_f32_e32 v38, v38, v34
	v_mul_f32_e32 v39, v39, v35
	v_mul_f32_e32 v40, v40, v36
	v_mul_f32_e32 v41, v41, v37
	v_exp_f32_e32 v38, v38
	v_exp_f32_e32 v39, v39
	v_exp_f32_e32 v40, v40
	v_exp_f32_e32 v41, v41
	v_add_f32_e32 v38, 1.0, v38
	v_add_f32_e32 v39, 1.0, v39
	v_add_f32_e32 v40, 1.0, v40
	v_add_f32_e32 v41, 1.0, v41
	v_rcp_f32_e32 v38, v38
	v_rcp_f32_e32 v39, v39
	v_rcp_f32_e32 v40, v40
	v_rcp_f32_e32 v41, v41
	v_mul_f32_e32 v34, v38, v34
	v_mul_f32_e32 v35, v39, v35
	v_mul_f32_e32 v36, v40, v36
	v_mul_f32_e32 v37, v41, v37
	v_mul_f32_e32 v46, v138, v34
	v_mul_f32_e32 v47, v139, v35
	v_mul_f32_e32 v48, v140, v36
	v_mul_f32_e32 v49, v141, v37
	v_cvt_pk_bf16_f32 v50, v46, v47
	v_cvt_pk_bf16_f32 v51, v48, v49
	global_store_dwordx2 v182, v[50:51], s[12:13] offset:448
	v_lshlrev_b32_e32 v34, 16, v202
	v_and_b32_e32 v35, 0xffff0000, v202
	v_lshlrev_b32_e32 v36, 16, v203
	v_and_b32_e32 v37, 0xffff0000, v203
	v_mul_f32_e32 v38, v34, v34
	v_mul_f32_e32 v39, v35, v35
	v_mul_f32_e32 v40, v36, v36
	v_mul_f32_e32 v41, v37, v37
	v_fmaak_f32 v38, v38, v197, 0xc0135761
	v_fmaak_f32 v39, v39, v197, 0xc0135761
	v_fmaak_f32 v40, v40, v197, 0xc0135761
	v_fmaak_f32 v41, v41, v197, 0xc0135761
	v_mul_f32_e32 v38, v38, v34
	v_mul_f32_e32 v39, v39, v35
	v_mul_f32_e32 v40, v40, v36
	v_mul_f32_e32 v41, v41, v37
	v_exp_f32_e32 v38, v38
	v_exp_f32_e32 v39, v39
	v_exp_f32_e32 v40, v40
	v_exp_f32_e32 v41, v41
	v_add_f32_e32 v38, 1.0, v38
	v_add_f32_e32 v39, 1.0, v39
	v_add_f32_e32 v40, 1.0, v40
	v_add_f32_e32 v41, 1.0, v41
	v_rcp_f32_e32 v38, v38
	v_rcp_f32_e32 v39, v39
	v_rcp_f32_e32 v40, v40
	v_rcp_f32_e32 v41, v41
	v_mul_f32_e32 v34, v38, v34
	v_mul_f32_e32 v35, v39, v35
	v_mul_f32_e32 v36, v40, v36
	v_mul_f32_e32 v37, v41, v37
	v_mul_f32_e32 v46, v160, v34
	v_mul_f32_e32 v47, v161, v35
	v_mul_f32_e32 v48, v162, v36
	v_mul_f32_e32 v49, v163, v37
	v_cvt_pk_bf16_f32 v50, v46, v47
	v_cvt_pk_bf16_f32 v51, v48, v49
	global_store_dwordx2 v182, v[50:51], s[12:13] offset:480
	s_add_i32 s2, s2, s3
	s_cmpk_lt_i32 s2, 0x100
	s_waitcnt lgkmcnt(0)
	s_barrier
	s_cbranch_scc1 .LBB0_330
	s_setprio 0
